# dilated item order: XCD-contiguous item ranges with workgroup-consecutive query blocks
# speedup vs baseline: 1.0020x; 1.0020x over previous
; DI int otid() { int t = threadIdx.x; asm volatile("" : "+v"(t)); return t; }
; DI void swin_attn_item(KP p, int item, u16* sm) {
;   const int tid = otid(), lane = tid & 63, w = __builtin_amdgcn_readfirstlane(tid >> 6), r = lane & 31, hh = lane >> 5;
;   u16* Ks = sm; u16* Vs = sm + 4 * KS_BUF;
;   const int bhp = item >> 6, sub = item & 63;
;   const int pat = bhp % 3, bh = bhp / 3, head = bh % 6, b = bh / 6;
;   const int sh = 2 * pat, L = S >> sh;
;   const int cls = sub >> (6 - sh), pb = sub & ((64 >> sh) - 1);
;   const int P = pb * 256;
; DI void phase_local(KP p, int layer, u16* sm) {
;     ...
;     if (it < N_DIL) swin_attn_item(p, (it & 7) * (N_DIL / 8) + (it >> 3), sm);
.LBB0_325:
	s_mov_b32 s6, s23
	s_mov_b32 s101, 0
	s_cmpk_lg_u32 s74, 0x100
	s_cbranch_scc1 .Ldil_item_known
	s_lshr_b32 s6, s2, 3
	s_mul_i32 s6, s6, 9
	s_and_b32 s7, s2, 7
	s_mulk_i32 s7, 0x120
	s_add_i32 s6, s6, s7
	s_lshr_b32 s101, s23, 8
	s_add_i32 s6, s6, s101
